# XCD seam: waiters poll the arrival counter itself against (seams so far) x (workgroups per XCD); no returning atomic, no generation word
# baseline (speedup 1.0000x reference)
; __device__ __forceinline__ unsigned xb_ld(unsigned* p)              { return __hip_atomic_load(p, __ATOMIC_RELAXED, __HIP_MEMORY_SCOPE_AGENT); }
; __device__ __forceinline__ unsigned xb_add(unsigned* p, unsigned v) { return __hip_atomic_fetch_add(p, v, __ATOMIC_RELAXED, __HIP_MEMORY_SCOPE_AGENT); }
; #define XB_SPIN(cond, bar) do { unsigned _sp = 0; while (cond) { __builtin_amdgcn_s_sleep(1); \
;     if ((++_sp & 255u) == 0u) { if (xb_ld(&(bar)[XB_TMO])) break; if (_sp > XB_SPIN_CAP) { atomicAdd(&(bar)[XB_TMO], 1u); break; } } } } while (0)
; __device__ __forceinline__ void xcc_barrier(unsigned* bar, unsigned x, unsigned nloc) {
;     asm volatile("s_waitcnt vmcnt(0)" ::: "memory");
;     __syncthreads();
;     if (threadIdx.x == 0) {
;         __builtin_amdgcn_s_waitcnt(0);
;         const unsigned old = xb_add(&bar[XL_SUB(x)], 1u), gen = old / nloc;
;         if (old + 1u == (gen + 1u) * nloc) xb_add(&bar[XL_GEN(x)], 1u); else XB_SPIN(xb_ld(&bar[XL_GEN(x)]) == gen, bar);
;         __builtin_amdgcn_fence(__ATOMIC_ACQUIRE, "agent");
;         asm volatile("s_waitcnt vmcnt(0)" ::: "memory");
;     }
;     __syncthreads();
; }
.LBB0_70:
	s_and_b64 vcc, exec, s[0:1]
	s_cbranch_vccz .LBB0_88
	s_waitcnt vmcnt(0)
	s_waitcnt lgkmcnt(0)
	v_readfirstlane_b32 s14, v3
	v_readfirstlane_b32 s15, v2
	s_barrier
	s_and_saveexec_b64 s[0:1], s[60:61]
	s_cbranch_execz .LBB0_87
	v_readlane_b32 s4, v254, 22
	s_lshl_b32 s4, s4, 8
	s_and_b32 s4, s4, 0x700
	s_add_u32 s4, s15, s4
	s_addc_u32 s5, s14, 0
	v_mov_b32_e32 v0, s4
	v_add_co_u32_e32 v2, vcc, 0x19704000, v0
	v_mov_b32_e32 v0, s5
	s_nop 0
	v_addc_co_u32_e32 v3, vcc, 0, v0, vcc
	s_waitcnt vmcnt(0) expcnt(0) lgkmcnt(0)
	buffer_inv sc1
	flat_atomic_add v[2:3], v223
	v_readlane_b32 s4, v254, 21
	s_mov_b32 s5, 0
	s_nop 2
	s_mul_i32 s4, s4, s65
.Lxcc_poll:
	flat_load_dword v0, v[2:3] sc1
	s_waitcnt vmcnt(0) lgkmcnt(0)
	v_readfirstlane_b32 s6, v0
	s_nop 3
	s_cmp_ge_u32 s6, s4
	s_cbranch_scc1 .Lxcc_done
	s_sleep 1
	s_add_i32 s5, s5, 1
	s_cmp_lt_u32 s5, 0x40000
	s_cbranch_scc1 .Lxcc_poll
.Lxcc_done:
.LBB0_87:
	s_or_b64 exec, exec, s[0:1]
	s_barrier
